# attention NOMAX units: static s_setprio 1 for waves 4-7 removed (equal priority) after the DMA-interleave restructuring
# baseline (speedup 1.0000x reference)
; template <bool DIFF, bool NOMAX>
; DI void unit(LAS unsigned char* lds, const Tensors& Tn, int b, int hd, int qb) {
;     ...
;     const int tid = tid_, w = __builtin_amdgcn_readfirstlane(tid >> 6), lane = tid & 63, r = lane & 31, h = lane >> 5;
;     const int wq = DIFF ? (w & 3) : w, map = DIFF ? (w >> 2) : 0;
;     const int q0 = DIFF ? qb * 128 + 32 * wq : qb * 256 + 32 * wq;
;     const int need = (q0 >> 6) + 1;
;     const int ntiles = DIFF ? 2 * qb + 2 : 4 * qb + 4;
;     int jst = 0, jbeg = 0;
;     const float sl2 = DIFF ? __builtin_amdgcn_exp2f(-(float)(hd + 1)) * LOG2E : 0.f;
;     if (DIFF) {
;         float wd[2];
; #pragma unroll
;         for (int mp = 0; mp < 2; ++mp) { const unsigned* nq = Tn.nrm + (((b * 8 + hd) * 2 + mp) * 2 + 0) * 4; const unsigned* nk = nq + 4;
;             const float sq = (__builtin_bit_cast(float, nq[0]) + __builtin_bit_cast(float, nq[1])) + (__builtin_bit_cast(float, nq[2]) + __builtin_bit_cast(float, nq[3]));
;             const float sk = (__builtin_bit_cast(float, nk[0]) + __builtin_bit_cast(float, nk[1])) + (__builtin_bit_cast(float, nk[2]) + __builtin_bit_cast(float, nk[3]));
;             const float B2 = __builtin_sqrtf(sq * sk) * 1.02f;
;             wd[mp] = (152.0f + 2.0f * B2) / sl2; }
;         const float lim = (float)(q0 - 63) - wd[map], limb = (float)(qb * 128 - 63) - __builtin_fmaxf(wd[0], wd[1]);
;         jst = lim > 0.f ? (int)__builtin_ceilf(lim * (1.0f / 64.0f)) : 0; jbeg = limb > 0.f ? (int)__builtin_ceilf(limb * (1.0f / 64.0f)) : 0;
;         jst = __builtin_amdgcn_readfirstlane(jst); jbeg = __builtin_amdgcn_readfirstlane(jbeg);
;         if (jst < jbeg) jst = jbeg;
;     }
;     const size_t tok0 = (size_t)b * SEQ;
;     if (w >= 4) __builtin_amdgcn_s_setprio(1);
.LBB0_689:
	s_and_b64 vcc, exec, s[58:59]
	s_cbranch_vccz .LBB0_819
	v_mov_b32_e32 v130, v242
	global_load_dwordx4 v[2:5], v1, s[56:57]
	global_load_dwordx4 v[6:9], v1, s[56:57] offset:16
	global_load_dwordx4 v[10:13], v1, s[56:57] offset:32
	global_load_dwordx4 v[14:17], v1, s[56:57] offset:48
	v_readfirstlane_b32 s14, v130
	s_ashr_i32 s25, s14, 6
	s_lshl_b32 s4, s25, 5
	s_and_b32 s72, s4, 0x60
	s_or_b32 s24, s72, s85
	s_sub_i32 s4, s24, 63
	v_cvt_f32_i32_e32 v0, s4
	s_ashr_i32 s27, s14, 8
	s_cmp_eq_u32 s27, 1
	s_waitcnt vmcnt(3)
	v_mov_b32_e32 v18, v2
	s_waitcnt vmcnt(2)
	v_mov_b32_e32 v19, v6
	v_mov_b32_e32 v6, v3
	v_mov_b32_e32 v2, v4
	v_mov_b32_e32 v3, v8
	v_mov_b32_e32 v8, v5
	s_waitcnt vmcnt(1)
	v_mov_b32_e32 v4, v10
	s_waitcnt vmcnt(0)
	v_mov_b32_e32 v5, v14
	v_mov_b32_e32 v14, v11
	v_mov_b32_e32 v10, v12
	v_mov_b32_e32 v11, v16
	v_mov_b32_e32 v16, v13
	v_pk_add_f32 v[6:7], v[18:19], v[6:7]
	v_pk_add_f32 v[2:3], v[2:3], v[8:9]
	v_pk_add_f32 v[4:5], v[4:5], v[14:15]
	v_pk_add_f32 v[8:9], v[10:11], v[16:17]
	v_pk_add_f32 v[2:3], v[6:7], v[2:3]
	v_pk_add_f32 v[4:5], v[4:5], v[8:9]
	v_mul_f32_e32 v2, v2, v3
	v_mul_f32_e32 v3, v4, v5
	v_mul_f32_e32 v4, 0x4f800000, v2
	v_cmp_gt_f32_e32 vcc, s3, v2
	v_mul_f32_e32 v5, 0x4f800000, v3
	v_cmp_gt_f32_e64 s[4:5], s3, v3
	v_cndmask_b32_e32 v2, v2, v4, vcc
	v_sqrt_f32_e32 v4, v2
	v_cndmask_b32_e64 v3, v3, v5, s[4:5]
	v_sqrt_f32_e32 v5, v3
	v_add_u32_e32 v6, -1, v4
	v_fma_f32 v10, -v6, v4, v2
	v_add_u32_e32 v8, -1, v5
	v_add_u32_e32 v7, 1, v4
	v_fma_f32 v12, -v8, v5, v3
	v_cmp_ge_f32_e64 s[6:7], 0, v10
	v_add_u32_e32 v9, 1, v5
	v_fma_f32 v11, -v7, v4, v2
	v_cndmask_b32_e64 v4, v4, v6, s[6:7]
	v_cmp_ge_f32_e64 s[6:7], 0, v12
	v_fma_f32 v13, -v9, v5, v3
	s_nop 0
	v_cndmask_b32_e64 v5, v5, v8, s[6:7]
	v_cmp_lt_f32_e64 s[6:7], 0, v11
	s_nop 1
	v_cndmask_b32_e64 v4, v4, v7, s[6:7]
	v_cmp_lt_f32_e64 s[6:7], 0, v13
	v_mul_f32_e32 v6, 0x37800000, v4
	v_cndmask_b32_e32 v4, v4, v6, vcc
	v_cndmask_b32_e64 v5, v5, v9, s[6:7]
	v_mul_f32_e32 v7, 0x37800000, v5
	v_cmp_class_f32_e32 vcc, v2, v250
	v_cndmask_b32_e64 v5, v5, v7, s[4:5]
	s_mov_b32 s4, 0x3f828f5c
	v_cndmask_b32_e32 v2, v4, v2, vcc
	v_cmp_class_f32_e32 vcc, v3, v250
	s_nop 1
	v_cndmask_b32_e32 v3, v5, v3, vcc
	v_pk_mul_f32 v[2:3], v[2:3], s[4:5] op_sel_hi:[1,0]
	s_nop 0
	v_pk_fma_f32 v[2:3], v[2:3], 2.0, s[16:17] op_sel_hi:[1,0,0]
	s_nop 0
	v_div_scale_f32 v4, s[4:5], v198, v198, v3
	v_div_scale_f32 v6, s[4:5], v198, v198, v2
	v_rcp_f32_e32 v7, v4
	v_rcp_f32_e32 v8, v6
	v_div_scale_f32 v5, vcc, v3, v198, v3
	v_fma_f32 v10, -v4, v7, 1.0
	v_fma_f32 v11, -v6, v8, 1.0
	v_fmac_f32_e32 v7, v10, v7
	v_div_scale_f32 v9, s[4:5], v2, v198, v2
	v_fmac_f32_e32 v8, v11, v8
	v_mul_f32_e32 v10, v5, v7
	v_mul_f32_e32 v11, v9, v8
	v_fma_f32 v12, -v4, v10, v5
	v_fma_f32 v13, -v6, v11, v9
	v_fmac_f32_e32 v10, v12, v7
	v_fmac_f32_e32 v11, v13, v8
	v_fma_f32 v4, -v4, v10, v5
	v_fma_f32 v5, -v6, v11, v9
	v_div_fmas_f32 v4, v4, v7, v10
	s_mov_b64 vcc, s[4:5]
	v_div_fixup_f32 v3, v4, v198, v3
	v_div_fmas_f32 v4, v5, v8, v11
	s_cselect_b64 vcc, -1, 0
	s_sub_i32 s4, s85, 63
	v_cvt_f32_i32_e32 v5, s4
	v_div_fixup_f32 v2, v4, v198, v2
	v_cndmask_b32_e32 v4, v2, v3, vcc
	v_max_f32_e32 v2, v2, v3
	v_sub_f32_e32 v0, v0, v4
	v_mul_f32_e32 v3, 0x3c800000, v0
	v_sub_f32_e32 v2, v5, v2
	v_ceil_f32_e32 v3, v3
	v_mul_f32_e32 v4, 0x3c800000, v2
	v_cvt_i32_f32_e32 v3, v3
	v_ceil_f32_e32 v4, v4
	v_cvt_i32_f32_e32 v4, v4
	v_cmp_lt_f32_e32 vcc, 0, v0
	s_cmp_lt_i32 s25, 4
	s_nop 0
	v_cndmask_b32_e32 v0, 0, v3, vcc
	v_cmp_lt_f32_e32 vcc, 0, v2
	v_readfirstlane_b32 s26, v0
	s_nop 0
	v_cndmask_b32_e32 v0, 0, v4, vcc
	s_nop 0
	v_readfirstlane_b32 s82, v0
	s_cbranch_scc1 .LBB0_692
	s_setprio 0

; template <bool DIFF, bool NOMAX>
; DI void unit(LAS unsigned char* lds, const Tensors& Tn, int b, int hd, int qb) {
;     ...
;     int tid_ = threadIdx.x; asm volatile("" : "+v"(tid_));
;     const int tid = tid_, w = __builtin_amdgcn_readfirstlane(tid >> 6), lane = tid & 63, r = lane & 31, h = lane >> 5;
;     const int wq = DIFF ? (w & 3) : w, map = DIFF ? (w >> 2) : 0;
;     const int q0 = DIFF ? qb * 128 + 32 * wq : qb * 256 + 32 * wq;
;     const int need = (q0 >> 6) + 1;
;     const int ntiles = DIFF ? 2 * qb + 2 : 4 * qb + 4;
;     int jst = 0, jbeg = 0;
;     const float sl2 = DIFF ? __builtin_amdgcn_exp2f(-(float)(hd + 1)) * LOG2E : 0.f;
;     if (DIFF) {
;         float wd[2];
; #pragma unroll
;         for (int mp = 0; mp < 2; ++mp) { const unsigned* nq = Tn.nrm + (((b * 8 + hd) * 2 + mp) * 2 + 0) * 4; const unsigned* nk = nq + 4;
;             const float sq = (__builtin_bit_cast(float, nq[0]) + __builtin_bit_cast(float, nq[1])) + (__builtin_bit_cast(float, nq[2]) + __builtin_bit_cast(float, nq[3]));
;             const float sk = (__builtin_bit_cast(float, nk[0]) + __builtin_bit_cast(float, nk[1])) + (__builtin_bit_cast(float, nk[2]) + __builtin_bit_cast(float, nk[3]));
;             const float B2 = __builtin_sqrtf(sq * sk) * 1.02f;
;             wd[mp] = (152.0f + 2.0f * B2) / sl2; }
;         const float lim = (float)(q0 - 63) - wd[map], limb = (float)(qb * 128 - 63) - __builtin_fmaxf(wd[0], wd[1]);
;         jst = lim > 0.f ? (int)__builtin_ceilf(lim * (1.0f / 64.0f)) : 0; jbeg = limb > 0.f ? (int)__builtin_ceilf(limb * (1.0f / 64.0f)) : 0;
;         jst = __builtin_amdgcn_readfirstlane(jst); jbeg = __builtin_amdgcn_readfirstlane(jbeg);
;         if (jst < jbeg) jst = jbeg;
;     }
;     const size_t tok0 = (size_t)b * SEQ;
;     if (w >= 4) __builtin_amdgcn_s_setprio(1);
.LBB0_1287:
	s_and_b64 vcc, exec, s[6:7]
	s_cbranch_vccz .LBB0_1040
	v_mov_b32_e32 v24, v242
	s_nop 0
	v_readfirstlane_b32 s4, v24
	s_ashr_i32 s17, s4, 6
	s_cmp_lt_i32 s17, 4
	s_cbranch_scc1 .LBB0_1290
	s_setprio 0

; template <bool DIFF, bool NOMAX>
; DI void unit(LAS unsigned char* lds, const Tensors& Tn, int b, int hd, int qb) {
;     ...
;     int tid_ = threadIdx.x; asm volatile("" : "+v"(tid_));
;     const int tid = tid_, w = __builtin_amdgcn_readfirstlane(tid >> 6), lane = tid & 63, r = lane & 31, h = lane >> 5;
;     const int wq = DIFF ? (w & 3) : w, map = DIFF ? (w >> 2) : 0;
;     const int q0 = DIFF ? qb * 128 + 32 * wq : qb * 256 + 32 * wq;
;     const int need = (q0 >> 6) + 1;
;     const int ntiles = DIFF ? 2 * qb + 2 : 4 * qb + 4;
;     int jst = 0, jbeg = 0;
;     const float sl2 = DIFF ? __builtin_amdgcn_exp2f(-(float)(hd + 1)) * LOG2E : 0.f;
;     if (DIFF) {
;         float wd[2];
; #pragma unroll
;         for (int mp = 0; mp < 2; ++mp) { const unsigned* nq = Tn.nrm + (((b * 8 + hd) * 2 + mp) * 2 + 0) * 4; const unsigned* nk = nq + 4;
;             const float sq = (__builtin_bit_cast(float, nq[0]) + __builtin_bit_cast(float, nq[1])) + (__builtin_bit_cast(float, nq[2]) + __builtin_bit_cast(float, nq[3]));
;             const float sk = (__builtin_bit_cast(float, nk[0]) + __builtin_bit_cast(float, nk[1])) + (__builtin_bit_cast(float, nk[2]) + __builtin_bit_cast(float, nk[3]));
;             const float B2 = __builtin_sqrtf(sq * sk) * 1.02f;
;             wd[mp] = (152.0f + 2.0f * B2) / sl2; }
;         const float lim = (float)(q0 - 63) - wd[map], limb = (float)(qb * 128 - 63) - __builtin_fmaxf(wd[0], wd[1]);
;     ...
;     __builtin_amdgcn_s_setprio(0);
;     int tid2_ = threadIdx.x; asm volatile("" : "+v"(tid2_));
;     const int lane2 = tid2_ & 63, w2 = __builtin_amdgcn_readfirstlane(tid2_ >> 6), wq2 = DIFF ? (w2 & 3) : w2, map2 = DIFF ? (w2 >> 2) : 0;
;     const int r2 = lane2 & 31, h2 = lane2 >> 5, q02 = DIFF ? qb * 128 + 32 * wq2 : qb * 256 + 32 * wq2;
;     const float ltot = lrow + shx<32>(lrow, lane2);
;     const float inv = 1.0f / ltot;
;     if (!DIFF) {
;         bf16_t* yp = Tn.Y + (tok0 + q02 + r2) * 2048 + hd * 128 + 4 * h2;
; #pragma unroll
;         for (int dt = 0; dt < NDT; ++dt)
; #pragma unroll
;             for (int g = 0; g < 4; ++g) { u32x2 pk; pk.x = cvtpk(o[dt][4 * g] * inv, o[dt][4 * g + 1] * inv); pk.y = cvtpk(o[dt][4 * g + 2] * inv, o[dt][4 * g + 3] * inv);
;                 *(u32x2*)(yp + 32 * dt + 8 * g) = pk; }
.LBB0_1400:
	s_setprio 0
	v_mov_b32_e32 v0, v242
	s_nop 0
	v_lshlrev_b32_e32 v2, 2, v0
	v_bitop3_b32 v2, v2, s97, v189 bitop3:0x6c
	ds_bpermute_b32 v2, v2, v172
	v_readfirstlane_b32 s4, v0
	s_ashr_i32 s4, s4, 1
	s_and_b32 s6, s4, 0xffffffe0
	s_add_i32 s6, s6, s28
	s_waitcnt lgkmcnt(0)
	v_add_f32_e32 v2, v172, v2
	v_div_scale_f32 v3, s[4:5], v2, v2, 1.0
	v_rcp_f32_e32 v4, v3
	v_div_scale_f32 v5, vcc, 1.0, v2, 1.0
	s_ashr_i32 s4, s6, 31
	v_fma_f32 v6, -v3, v4, 1.0
	v_fmac_f32_e32 v4, v6, v4
	v_mul_f32_e32 v6, v5, v4
	v_fma_f32 v7, -v3, v6, v5
	v_fmac_f32_e32 v6, v7, v4
	s_add_u32 s5, s62, s6
	v_fma_f32 v3, -v3, v6, v5
	s_addc_u32 s4, s63, s4
	v_div_fmas_f32 v3, v3, v4, v6
	v_and_or_b32 v4, v0, 31, s5
	v_mov_b32_e32 v5, s4
	v_lshlrev_b64 v[4:5], 12, v[4:5]
	s_lshl_b32 s68, s90, 7
	v_div_fixup_f32 v2, v3, v2, 1.0
	v_lshl_add_u64 v[4:5], s[44:45], 0, v[4:5]
	s_ashr_i32 s69, s68, 31
	v_lshrrev_b32_e32 v0, 2, v0
	v_lshl_add_u64 v[4:5], s[68:69], 1, v[4:5]
	v_and_b32_e32 v0, 8, v0
	v_pk_mul_f32 v[6:7], v[64:65], v[2:3] op_sel_hi:[1,0]
	v_pk_mul_f32 v[8:9], v[66:67], v[2:3] op_sel_hi:[1,0]
	v_lshl_add_u64 v[4:5], v[4:5], 0, v[0:1]
	v_cvt_pk_bf16_f32 v6, v6, v7
	v_cvt_pk_bf16_f32 v7, v8, v9
	global_store_dwordx2 v[4:5], v[6:7], off
	v_pk_mul_f32 v[6:7], v[68:69], v[2:3] op_sel_hi:[1,0]
	v_pk_mul_f32 v[8:9], v[70:71], v[2:3] op_sel_hi:[1,0]
	v_cvt_pk_bf16_f32 v6, v6, v7
	v_cvt_pk_bf16_f32 v7, v8, v9
	global_store_dwordx2 v[4:5], v[6:7], off offset:16
	v_pk_mul_f32 v[6:7], v[72:73], v[2:3] op_sel_hi:[1,0]
	v_pk_mul_f32 v[8:9], v[74:75], v[2:3] op_sel_hi:[1,0]
	v_cvt_pk_bf16_f32 v6, v6, v7
	v_cvt_pk_bf16_f32 v7, v8, v9
	global_store_dwordx2 v[4:5], v[6:7], off offset:32
	v_pk_mul_f32 v[6:7], v[76:77], v[2:3] op_sel_hi:[1,0]
	v_pk_mul_f32 v[8:9], v[78:79], v[2:3] op_sel_hi:[1,0]
	v_cvt_pk_bf16_f32 v6, v6, v7
	v_cvt_pk_bf16_f32 v7, v8, v9
	global_store_dwordx2 v[4:5], v[6:7], off offset:48
	v_pk_mul_f32 v[6:7], v[48:49], v[2:3] op_sel_hi:[1,0]
	v_pk_mul_f32 v[8:9], v[50:51], v[2:3] op_sel_hi:[1,0]
	v_cvt_pk_bf16_f32 v6, v6, v7
	v_cvt_pk_bf16_f32 v7, v8, v9
	global_store_dwordx2 v[4:5], v[6:7], off offset:64
	v_pk_mul_f32 v[6:7], v[52:53], v[2:3] op_sel_hi:[1,0]
	v_pk_mul_f32 v[8:9], v[54:55], v[2:3] op_sel_hi:[1,0]
	v_cvt_pk_bf16_f32 v6, v6, v7
	v_cvt_pk_bf16_f32 v7, v8, v9
	global_store_dwordx2 v[4:5], v[6:7], off offset:80
	v_pk_mul_f32 v[6:7], v[56:57], v[2:3] op_sel_hi:[1,0]
	v_pk_mul_f32 v[8:9], v[58:59], v[2:3] op_sel_hi:[1,0]
	v_cvt_pk_bf16_f32 v6, v6, v7
	v_cvt_pk_bf16_f32 v7, v8, v9
	global_store_dwordx2 v[4:5], v[6:7], off offset:96
	v_pk_mul_f32 v[6:7], v[60:61], v[2:3] op_sel_hi:[1,0]
	v_pk_mul_f32 v[8:9], v[62:63], v[2:3] op_sel_hi:[1,0]
	v_cvt_pk_bf16_f32 v6, v6, v7
	v_cvt_pk_bf16_f32 v7, v8, v9
	global_store_dwordx2 v[4:5], v[6:7], off offset:112
	v_pk_mul_f32 v[6:7], v[32:33], v[2:3] op_sel_hi:[1,0]
	v_pk_mul_f32 v[8:9], v[34:35], v[2:3] op_sel_hi:[1,0]
	v_cvt_pk_bf16_f32 v6, v6, v7
	v_cvt_pk_bf16_f32 v7, v8, v9
	global_store_dwordx2 v[4:5], v[6:7], off offset:128
	v_pk_mul_f32 v[6:7], v[36:37], v[2:3] op_sel_hi:[1,0]
	v_pk_mul_f32 v[8:9], v[38:39], v[2:3] op_sel_hi:[1,0]
	v_cvt_pk_bf16_f32 v6, v6, v7
	v_cvt_pk_bf16_f32 v7, v8, v9
	global_store_dwordx2 v[4:5], v[6:7], off offset:144
	v_pk_mul_f32 v[6:7], v[40:41], v[2:3] op_sel_hi:[1,0]
	v_pk_mul_f32 v[8:9], v[42:43], v[2:3] op_sel_hi:[1,0]
	v_cvt_pk_bf16_f32 v6, v6, v7
	v_cvt_pk_bf16_f32 v7, v8, v9
	global_store_dwordx2 v[4:5], v[6:7], off offset:160
	v_pk_mul_f32 v[6:7], v[44:45], v[2:3] op_sel_hi:[1,0]
	v_pk_mul_f32 v[8:9], v[46:47], v[2:3] op_sel_hi:[1,0]
	v_cvt_pk_bf16_f32 v6, v6, v7
	v_cvt_pk_bf16_f32 v7, v8, v9
	global_store_dwordx2 v[4:5], v[6:7], off offset:176
	v_pk_mul_f32 v[6:7], v[16:17], v[2:3] op_sel_hi:[1,0]
	v_pk_mul_f32 v[8:9], v[18:19], v[2:3] op_sel_hi:[1,0]
	v_cvt_pk_bf16_f32 v6, v6, v7
	v_cvt_pk_bf16_f32 v7, v8, v9
	global_store_dwordx2 v[4:5], v[6:7], off offset:192
	v_pk_mul_f32 v[6:7], v[20:21], v[2:3] op_sel_hi:[1,0]
	v_pk_mul_f32 v[8:9], v[22:23], v[2:3] op_sel_hi:[1,0]
	v_cvt_pk_bf16_f32 v6, v6, v7
	v_cvt_pk_bf16_f32 v7, v8, v9
	global_store_dwordx2 v[4:5], v[6:7], off offset:208
	v_pk_mul_f32 v[6:7], v[24:25], v[2:3] op_sel_hi:[1,0]
	v_pk_mul_f32 v[8:9], v[26:27], v[2:3] op_sel_hi:[1,0]
	v_cvt_pk_bf16_f32 v6, v6, v7
	v_cvt_pk_bf16_f32 v7, v8, v9
	global_store_dwordx2 v[4:5], v[6:7], off offset:224
	v_pk_mul_f32 v[6:7], v[28:29], v[2:3] op_sel_hi:[1,0]
	v_pk_mul_f32 v[2:3], v[30:31], v[2:3] op_sel_hi:[1,0]
	v_cvt_pk_bf16_f32 v6, v6, v7
	v_cvt_pk_bf16_f32 v7, v2, v3
	v_mov_b32_e32 v26, v242
	global_store_dwordx2 v[4:5], v[6:7], off offset:240
	s_nop 0
	v_readfirstlane_b32 s4, v26
	s_ashr_i32 s11, s4, 6
	s_cmp_lt_i32 s11, 4
	s_cbranch_scc1 .LBB0_1402
	s_setprio 0
